# sample cross-attention item: 16 Q partial-sum loads in flight; f32->bf16 conversion tiles: 8 row loads in flight with counted waits (phase 0 loop and both phase-1 tail copies)
# speedup vs baseline: 1.0099x; 1.0099x over previous
.LBB0_87:
	v_lshlrev_b32_e32 v0, 3, v18
	v_and_b32_e32 v0, 56, v0
	s_add_i32 s35, s35, s29
	v_mad_u32_u24 v19, v0, s15, 0
	s_ashr_i32 s29, s28, 31
	v_ashrrev_i32_e32 v16, 3, v18
	s_lshl_b64 s[18:19], s[28:29], 1
	v_lshlrev_b32_e32 v6, 1, v0
	v_lshl_add_u32 v0, v16, 2, v19
	s_waitcnt lgkmcnt(0)
	s_barrier
	s_add_u32 s18, s68, s18
	ds_read_b32 v1, v0
	ds_read_b32 v2, v0 offset:1028
	ds_read_b32 v3, v0 offset:2056
	ds_read_b32 v17, v0 offset:3084
	ds_read_b32 v20, v0 offset:4112
	ds_read_b32 v21, v0 offset:5140
	ds_read_b32 v24, v0 offset:6168
	ds_read_b32 v25, v0 offset:7196
	s_addc_u32 s19, s69, s19
	v_lshl_add_u64 v[4:5], s[18:19], 0, v[6:7]
	v_add_u32_e32 v6, 0x200, v18
	v_ashrrev_i32_e32 v6, 3, v6
	s_waitcnt lgkmcnt(6)
	v_cvt_pk_bf16_f32 v0, v1, v2
	s_waitcnt lgkmcnt(2)
	v_cvt_pk_bf16_f32 v2, v20, v21
	v_add_u32_e32 v16, s35, v16
	v_lshl_add_u32 v20, v6, 2, v19
	v_cvt_pk_bf16_f32 v1, v3, v17
	s_waitcnt lgkmcnt(0)
	v_cvt_pk_bf16_f32 v3, v24, v25
	v_ashrrev_i32_e32 v17, 31, v16
	ds_read_b32 v21, v20
	ds_read_b32 v24, v20 offset:1028
	ds_read_b32 v25, v20 offset:2056
	ds_read_b32 v26, v20 offset:3084
	ds_read_b32 v27, v20 offset:4112
	ds_read_b32 v28, v20 offset:5140
	ds_read_b32 v29, v20 offset:6168
	ds_read_b32 v20, v20 offset:7196
	v_lshlrev_b64 v[16:17], 12, v[16:17]
	v_lshl_add_u64 v[16:17], v[4:5], 0, v[16:17]
	global_store_dwordx4 v[16:17], v[0:3], off
	v_add_u32_e32 v16, s35, v6
	v_add_u32_e32 v6, 0x400, v18
	v_ashrrev_i32_e32 v6, 3, v6
	s_waitcnt lgkmcnt(0)
	v_cvt_pk_bf16_f32 v3, v29, v20
	v_ashrrev_i32_e32 v17, 31, v16
	v_lshl_add_u32 v20, v6, 2, v19
	v_cvt_pk_bf16_f32 v0, v21, v24
	v_cvt_pk_bf16_f32 v1, v25, v26
	v_cvt_pk_bf16_f32 v2, v27, v28
	v_lshlrev_b64 v[16:17], 12, v[16:17]
	ds_read_b32 v21, v20
	ds_read_b32 v24, v20 offset:1028
	ds_read_b32 v25, v20 offset:2056
	ds_read_b32 v26, v20 offset:3084
	ds_read_b32 v27, v20 offset:4112
	ds_read_b32 v28, v20 offset:5140
	ds_read_b32 v29, v20 offset:6168
	ds_read_b32 v20, v20 offset:7196
	v_lshl_add_u64 v[16:17], v[4:5], 0, v[16:17]
	global_store_dwordx4 v[16:17], v[0:3], off
	v_add_u32_e32 v16, s35, v6
	v_ashrrev_i32_e32 v17, 31, v16
	v_lshlrev_b64 v[16:17], 12, v[16:17]
	s_waitcnt lgkmcnt(6)
	v_cvt_pk_bf16_f32 v0, v21, v24
	s_waitcnt lgkmcnt(4)
	v_cvt_pk_bf16_f32 v1, v25, v26
	s_waitcnt lgkmcnt(2)
	v_cvt_pk_bf16_f32 v2, v27, v28
	s_waitcnt lgkmcnt(0)
	v_cvt_pk_bf16_f32 v3, v29, v20
	v_lshl_add_u64 v[16:17], v[4:5], 0, v[16:17]
	global_store_dwordx4 v[16:17], v[0:3], off
	s_nop 1
	v_add_u32_e32 v0, 0x600, v18
	v_ashrrev_i32_e32 v0, 3, v0
	v_lshl_add_u32 v1, v0, 2, v19
	ds_read_b32 v2, v1
	ds_read_b32 v3, v1 offset:1028
	ds_read_b32 v6, v1 offset:2056
	ds_read_b32 v17, v1 offset:3084
	ds_read_b32 v18, v1 offset:4112
	ds_read_b32 v19, v1 offset:5140
	ds_read_b32 v20, v1 offset:6168
	ds_read_b32 v21, v1 offset:7196
	v_add_u32_e32 v16, s35, v0
	s_waitcnt lgkmcnt(4)
	v_cvt_pk_bf16_f32 v1, v6, v17
	v_ashrrev_i32_e32 v17, 31, v16
	v_lshlrev_b64 v[16:17], 12, v[16:17]
	v_cvt_pk_bf16_f32 v0, v2, v3
	s_waitcnt lgkmcnt(2)
	v_cvt_pk_bf16_f32 v2, v18, v19
	s_waitcnt lgkmcnt(0)
	v_cvt_pk_bf16_f32 v3, v20, v21
	v_lshl_add_u64 v[4:5], v[4:5], 0, v[16:17]
	global_store_dwordx4 v[4:5], v[0:3], off
	s_barrier
	s_load_dwordx2 s[18:19], s[80:81], 0x138
	s_waitcnt lgkmcnt(0)
	s_add_i32 s34, s34, s18
	s_cmpk_lt_i32 s34, 0x9a0
	s_cbranch_scc0 .LBB0_19

.LBB0_96:
	v_cvt_f32_u32_e32 v0, s28
	s_sub_i32 s38, 0, s28
	s_abs_i32 s19, s35
	s_ashr_i32 s18, s35, 31
	v_rcp_iflag_f32_e32 v0, v0
	v_mov_b32_e32 v18, v230
	v_mov_b32_e32 v2, 0
	v_mul_f32_e32 v0, 0x4f7ffffe, v0
	v_cvt_u32_f32_e32 v0, v0
	v_lshlrev_b32_e32 v1, 2, v18
	v_and_b32_e32 v1, 0xfc, v1
	v_lshlrev_b32_e32 v6, 2, v1
	v_readfirstlane_b32 vcc_lo, v0
	s_mul_i32 s38, s38, vcc_lo
	s_mul_hi_u32 s38, vcc_lo, s38
	s_add_i32 vcc_lo, vcc_lo, s38
	s_mul_hi_u32 s38, s19, vcc_lo
	s_mul_i32 vcc_lo, s38, s28
	s_sub_i32 s19, s19, vcc_lo
	s_add_i32 vcc_hi, s38, 1
	s_sub_i32 vcc_lo, s19, s28
	s_cmp_ge_u32 s19, s28
	s_cselect_b32 s38, vcc_hi, s38
	s_cselect_b32 s19, vcc_lo, s19
	s_add_i32 vcc_lo, s38, 1
	s_cmp_ge_u32 s19, s28
	s_cselect_b32 s19, vcc_lo, s38
	s_xor_b32 s19, s19, s18
	s_sub_i32 s18, s19, s18
	s_mul_i32 s19, s18, s28
	s_lshl_b32 s28, s18, 6
	s_sub_i32 s18, s35, s19
	s_lshl_b32 s35, s18, 8
	s_add_i32 s18, s35, s37
	s_ashr_i32 s19, s18, 31
	s_lshl_b64 s[18:19], s[18:19], 2
	s_add_u32 s18, s30, s18
	s_addc_u32 s19, s31, s19
	v_ashrrev_i32_e32 v19, 6, v18
	v_cmp_gt_u32_e32 vcc, s36, v1
	v_lshl_add_u64 v[16:17], s[18:19], 0, v[6:7]
	v_mov_b32_e32 v136, 0
	v_mov_b32_e32 v137, 0
	v_mov_b32_e32 v138, 0
	v_mov_b32_e32 v139, 0
	v_mov_b32_e32 v140, 0
	v_mov_b32_e32 v141, 0
	v_mov_b32_e32 v142, 0
	v_mov_b32_e32 v143, 0
	v_mov_b32_e32 v144, 0
	v_mov_b32_e32 v145, 0
	v_mov_b32_e32 v146, 0
	v_mov_b32_e32 v147, 0
	v_mov_b32_e32 v148, 0
	v_mov_b32_e32 v149, 0
	v_mov_b32_e32 v150, 0
	v_mov_b32_e32 v151, 0
	v_mov_b32_e32 v152, 0
	v_mov_b32_e32 v153, 0
	v_mov_b32_e32 v154, 0
	v_mov_b32_e32 v155, 0
	v_mov_b32_e32 v156, 0
	v_mov_b32_e32 v157, 0
	v_mov_b32_e32 v158, 0
	v_mov_b32_e32 v159, 0
	v_mov_b32_e32 v160, 0
	v_mov_b32_e32 v161, 0
	v_mov_b32_e32 v162, 0
	v_mov_b32_e32 v163, 0
	v_mov_b32_e32 v164, 0
	v_mov_b32_e32 v165, 0
	v_mov_b32_e32 v166, 0
	v_mov_b32_e32 v167, 0
	s_lshl_b64 s[100:101], s[26:27], 5
	s_and_saveexec_b64 s[18:19], vcc
	s_cbranch_execz .LconvP0_skip
	v_add_u32_e32 v2, s28, v19
	v_ashrrev_i32_e32 v3, 31, v2
	v_mul_lo_u32 v4, s26, v3
	v_mul_lo_u32 v5, s27, v2
	v_mad_u64_u32 v[2:3], s[30:31], s26, v2, 0
	v_add3_u32 v3, v3, v4, v5
	v_lshl_add_u64 v[2:3], v[2:3], 2, v[16:17]
	global_load_dwordx4 v[136:139], v[2:3], off
	v_lshl_add_u64 v[2:3], v[2:3], 0, s[100:101]
	global_load_dwordx4 v[140:143], v[2:3], off
	v_lshl_add_u64 v[2:3], v[2:3], 0, s[100:101]
	global_load_dwordx4 v[144:147], v[2:3], off
	v_lshl_add_u64 v[2:3], v[2:3], 0, s[100:101]
	global_load_dwordx4 v[148:151], v[2:3], off
	v_lshl_add_u64 v[2:3], v[2:3], 0, s[100:101]
	global_load_dwordx4 v[152:155], v[2:3], off
	v_lshl_add_u64 v[2:3], v[2:3], 0, s[100:101]
	global_load_dwordx4 v[156:159], v[2:3], off
	v_lshl_add_u64 v[2:3], v[2:3], 0, s[100:101]
	global_load_dwordx4 v[160:163], v[2:3], off
	v_lshl_add_u64 v[2:3], v[2:3], 0, s[100:101]
	global_load_dwordx4 v[164:167], v[2:3], off
.LconvP0_skip:
	s_or_b64 exec, exec, s[18:19]
	v_lshl_add_u32 v1, v1, 2, 0
	v_mul_lo_u32 v6, v19, s15
	v_add_u32_e32 v6, v1, v6
	s_waitcnt vmcnt(7)
	ds_write2_b32 v6, v136, v137 offset1:1
	ds_write2_b32 v6, v138, v139 offset0:2 offset1:3
	s_waitcnt vmcnt(6)
	v_add_u32_e32 v4, 0x2020, v6
	ds_write2_b32 v4, v140, v141 offset1:1
	ds_write2_b32 v4, v142, v143 offset0:2 offset1:3
	s_waitcnt vmcnt(5)
	v_add_u32_e32 v4, 0x4040, v6
	ds_write2_b32 v4, v144, v145 offset1:1
	ds_write2_b32 v4, v146, v147 offset0:2 offset1:3
	s_waitcnt vmcnt(4)
	v_add_u32_e32 v4, 0x6060, v6
	ds_write2_b32 v4, v148, v149 offset1:1
	ds_write2_b32 v4, v150, v151 offset0:2 offset1:3
	s_waitcnt vmcnt(3)
	v_add_u32_e32 v4, 0x8080, v6
	ds_write2_b32 v4, v152, v153 offset1:1
	ds_write2_b32 v4, v154, v155 offset0:2 offset1:3
	s_waitcnt vmcnt(2)
	v_add_u32_e32 v4, 0xa0a0, v6
	ds_write2_b32 v4, v156, v157 offset1:1
	ds_write2_b32 v4, v158, v159 offset0:2 offset1:3
	s_waitcnt vmcnt(1)
	v_add_u32_e32 v4, 0xc0c0, v6
	ds_write2_b32 v4, v160, v161 offset1:1
	ds_write2_b32 v4, v162, v163 offset0:2 offset1:3
	s_waitcnt vmcnt(0)
	v_add_u32_e32 v4, 0xe0e0, v6
	ds_write2_b32 v4, v164, v165 offset1:1
	ds_write2_b32 v4, v166, v167 offset0:2 offset1:3
	s_branch .LBB0_87

.LBB0_491:
	v_cvt_f32_u32_e32 v0, s14
	s_sub_i32 s28, 0, s14
	s_abs_i32 s19, s11
	s_ashr_i32 s18, s11, 31
	v_rcp_iflag_f32_e32 v0, v0
	v_mov_b32_e32 v8, v230
	v_mov_b32_e32 v2, 0
	v_mul_f32_e32 v0, 0x4f7ffffe, v0
	v_cvt_u32_f32_e32 v0, v0
	v_lshlrev_b32_e32 v1, 2, v8
	v_and_b32_e32 v1, 0xfc, v1
	v_cmp_gt_u32_e32 vcc, s15, v1
	v_readfirstlane_b32 s29, v0
	s_mul_i32 s28, s28, s29
	s_mul_hi_u32 s28, s29, s28
	s_add_i32 s29, s29, s28
	s_mul_hi_u32 s28, s19, s29
	s_mul_i32 s29, s28, s14
	s_sub_i32 s19, s19, s29
	s_add_i32 s33, s28, 1
	s_sub_i32 s29, s19, s14
	s_cmp_ge_u32 s19, s14
	s_cselect_b32 s28, s33, s28
	s_cselect_b32 s19, s29, s19
	s_add_i32 s29, s28, 1
	s_cmp_ge_u32 s19, s14
	s_cselect_b32 s19, s29, s28
	s_xor_b32 s19, s19, s18
	s_sub_i32 s18, s19, s18
	s_mul_i32 s14, s18, s14
	s_sub_i32 s11, s11, s14
	s_lshl_b32 s11, s11, 8
	s_add_i32 s56, s11, s17
	s_ashr_i32 s57, s56, 31
	s_lshl_b32 s58, s18, 6
	s_lshl_b64 s[14:15], s[56:57], 2
	s_add_u32 s14, s36, s14
	s_addc_u32 s15, s37, s15
	v_lshlrev_b32_e32 v128, 2, v1
	v_ashrrev_i32_e32 v9, 6, v8
	v_lshl_add_u64 v[6:7], s[14:15], 0, v[128:129]
	v_mov_b32_e32 v136, 0
	v_mov_b32_e32 v137, 0
	v_mov_b32_e32 v138, 0
	v_mov_b32_e32 v139, 0
	v_mov_b32_e32 v140, 0
	v_mov_b32_e32 v141, 0
	v_mov_b32_e32 v142, 0
	v_mov_b32_e32 v143, 0
	v_mov_b32_e32 v144, 0
	v_mov_b32_e32 v145, 0
	v_mov_b32_e32 v146, 0
	v_mov_b32_e32 v147, 0
	v_mov_b32_e32 v148, 0
	v_mov_b32_e32 v149, 0
	v_mov_b32_e32 v150, 0
	v_mov_b32_e32 v151, 0
	v_mov_b32_e32 v152, 0
	v_mov_b32_e32 v153, 0
	v_mov_b32_e32 v154, 0
	v_mov_b32_e32 v155, 0
	v_mov_b32_e32 v156, 0
	v_mov_b32_e32 v157, 0
	v_mov_b32_e32 v158, 0
	v_mov_b32_e32 v159, 0
	v_mov_b32_e32 v160, 0
	v_mov_b32_e32 v161, 0
	v_mov_b32_e32 v162, 0
	v_mov_b32_e32 v163, 0
	v_mov_b32_e32 v164, 0
	v_mov_b32_e32 v165, 0
	v_mov_b32_e32 v166, 0
	v_mov_b32_e32 v167, 0
	s_lshl_b64 s[100:101], s[26:27], 5
	s_and_saveexec_b64 s[36:37], vcc
	s_cbranch_execz .LconvA_skip
	v_add_u32_e32 v2, s58, v9
	v_ashrrev_i32_e32 v3, 31, v2
	v_mul_lo_u32 v4, s26, v3
	v_mul_lo_u32 v5, s27, v2
	v_mad_u64_u32 v[2:3], s[14:15], s26, v2, 0
	v_add3_u32 v3, v3, v4, v5
	v_lshl_add_u64 v[2:3], v[2:3], 2, v[6:7]
	global_load_dwordx4 v[136:139], v[2:3], off
	v_lshl_add_u64 v[2:3], v[2:3], 0, s[100:101]
	global_load_dwordx4 v[140:143], v[2:3], off
	v_lshl_add_u64 v[2:3], v[2:3], 0, s[100:101]
	global_load_dwordx4 v[144:147], v[2:3], off
	v_lshl_add_u64 v[2:3], v[2:3], 0, s[100:101]
	global_load_dwordx4 v[148:151], v[2:3], off
	v_lshl_add_u64 v[2:3], v[2:3], 0, s[100:101]
	global_load_dwordx4 v[152:155], v[2:3], off
	v_lshl_add_u64 v[2:3], v[2:3], 0, s[100:101]
	global_load_dwordx4 v[156:159], v[2:3], off
	v_lshl_add_u64 v[2:3], v[2:3], 0, s[100:101]
	global_load_dwordx4 v[160:163], v[2:3], off
	v_lshl_add_u64 v[2:3], v[2:3], 0, s[100:101]
	global_load_dwordx4 v[164:167], v[2:3], off
.LconvA_skip:
	s_or_b64 exec, exec, s[36:37]
	v_lshl_add_u32 v1, v1, 2, 0
	v_mul_lo_u32 v10, v9, s16
	v_add_u32_e32 v10, v1, v10
	s_waitcnt vmcnt(7)
	ds_write2_b32 v10, v136, v137 offset1:1
	ds_write2_b32 v10, v138, v139 offset0:2 offset1:3
	s_waitcnt vmcnt(6)
	v_add_u32_e32 v4, 0x2020, v10
	ds_write2_b32 v4, v140, v141 offset1:1
	ds_write2_b32 v4, v142, v143 offset0:2 offset1:3
	s_waitcnt vmcnt(5)
	v_add_u32_e32 v4, 0x4040, v10
	ds_write2_b32 v4, v144, v145 offset1:1
	ds_write2_b32 v4, v146, v147 offset0:2 offset1:3
	s_waitcnt vmcnt(4)
	v_add_u32_e32 v4, 0x6060, v10
	ds_write2_b32 v4, v148, v149 offset1:1
	ds_write2_b32 v4, v150, v151 offset0:2 offset1:3
	s_waitcnt vmcnt(3)
	v_add_u32_e32 v4, 0x8080, v10
	ds_write2_b32 v4, v152, v153 offset1:1
	ds_write2_b32 v4, v154, v155 offset0:2 offset1:3
	s_waitcnt vmcnt(2)
	v_add_u32_e32 v4, 0xa0a0, v10
	ds_write2_b32 v4, v156, v157 offset1:1
	ds_write2_b32 v4, v158, v159 offset0:2 offset1:3
	s_waitcnt vmcnt(1)
	v_add_u32_e32 v4, 0xc0c0, v10
	ds_write2_b32 v4, v160, v161 offset1:1
	ds_write2_b32 v4, v162, v163 offset0:2 offset1:3
	s_waitcnt vmcnt(0)
	v_add_u32_e32 v4, 0xe0e0, v10
	ds_write2_b32 v4, v164, v165 offset1:1
	ds_write2_b32 v4, v166, v167 offset0:2 offset1:3
	v_lshlrev_b32_e32 v0, 3, v8
	v_and_b32_e32 v0, 56, v0
	v_mad_u32_u24 v2, v0, s16, 0
	v_ashrrev_i32_e32 v1, 3, v8
	v_lshl_add_u32 v11, v1, 2, v2
	s_waitcnt lgkmcnt(0)
	s_barrier
	ds_read_b32 v3, v11
	ds_read_b32 v4, v11 offset:1028
	ds_read_b32 v5, v11 offset:2056
	ds_read_b32 v6, v11 offset:3084
	ds_read_b32 v7, v11 offset:4112
	ds_read_b32 v9, v11 offset:5140
	ds_read_b32 v10, v11 offset:6168
	ds_read_b32 v11, v11 offset:7196
	s_xor_b64 s[24:25], s[24:25], -1
	s_mov_b64 s[26:27], -1
	s_and_b64 vcc, exec, s[24:25]
	s_cbranch_vccz .LBB0_509
	v_add_u32_e32 v12, s56, v1
	v_lshlrev_b32_e32 v13, 1, v12
	v_and_b32_e32 v12, 0x7f, v12
	v_and_b32_e32 v13, 0xffffff00, v13
	v_or_b32_e32 v12, s9, v12
	v_add_u32_e32 v12, v12, v13
	s_mov_b64 s[26:27], 0

.LBB0_541:
	v_cvt_f32_u32_e32 v0, s13
	s_sub_i32 s19, 0, s13
	s_abs_i32 s18, s11
	s_ashr_i32 s7, s11, 31
	v_rcp_iflag_f32_e32 v0, v0
	v_mov_b32_e32 v8, v230
	v_mov_b32_e32 v2, 0
	v_mul_f32_e32 v0, 0x4f7ffffe, v0
	v_cvt_u32_f32_e32 v0, v0
	v_lshlrev_b32_e32 v1, 2, v8
	v_and_b32_e32 v1, 0xfc, v1
	v_lshlrev_b32_e32 v128, 2, v1
	v_readfirstlane_b32 s28, v0
	s_mul_i32 s19, s19, s28
	s_mul_hi_u32 s19, s28, s19
	s_add_i32 s28, s28, s19
	s_mul_hi_u32 s19, s18, s28
	s_mul_i32 s28, s19, s13
	s_sub_i32 s18, s18, s28
	s_add_i32 s29, s19, 1
	s_sub_i32 s28, s18, s13
	s_cmp_ge_u32 s18, s13
	s_cselect_b32 s19, s29, s19
	s_cselect_b32 s18, s28, s18
	s_add_i32 s28, s19, 1
	s_cmp_ge_u32 s18, s13
	s_cselect_b32 s18, s28, s19
	s_xor_b32 s18, s18, s7
	s_sub_i32 s7, s18, s7
	s_mul_i32 s13, s7, s13
	s_lshl_b32 s56, s7, 6
	s_sub_i32 s7, s11, s13
	s_lshl_b32 s7, s7, 8
	s_add_i32 s36, s7, s17
	s_ashr_i32 s37, s36, 31
	s_lshl_b64 s[18:19], s[36:37], 2
	s_add_u32 s18, s26, s18
	s_addc_u32 s19, s27, s19
	v_ashrrev_i32_e32 v9, 6, v8
	v_cmp_gt_u32_e32 vcc, s15, v1
	v_lshl_add_u64 v[6:7], s[18:19], 0, v[128:129]
	v_mov_b32_e32 v136, 0
	v_mov_b32_e32 v137, 0
	v_mov_b32_e32 v138, 0
	v_mov_b32_e32 v139, 0
	v_mov_b32_e32 v140, 0
	v_mov_b32_e32 v141, 0
	v_mov_b32_e32 v142, 0
	v_mov_b32_e32 v143, 0
	v_mov_b32_e32 v144, 0
	v_mov_b32_e32 v145, 0
	v_mov_b32_e32 v146, 0
	v_mov_b32_e32 v147, 0
	v_mov_b32_e32 v148, 0
	v_mov_b32_e32 v149, 0
	v_mov_b32_e32 v150, 0
	v_mov_b32_e32 v151, 0
	v_mov_b32_e32 v152, 0
	v_mov_b32_e32 v153, 0
	v_mov_b32_e32 v154, 0
	v_mov_b32_e32 v155, 0
	v_mov_b32_e32 v156, 0
	v_mov_b32_e32 v157, 0
	v_mov_b32_e32 v158, 0
	v_mov_b32_e32 v159, 0
	v_mov_b32_e32 v160, 0
	v_mov_b32_e32 v161, 0
	v_mov_b32_e32 v162, 0
	v_mov_b32_e32 v163, 0
	v_mov_b32_e32 v164, 0
	v_mov_b32_e32 v165, 0
	v_mov_b32_e32 v166, 0
	v_mov_b32_e32 v167, 0
	s_lshl_b64 s[100:101], s[24:25], 5
	s_and_saveexec_b64 s[26:27], vcc
	s_cbranch_execz .LconvB_skip
	v_add_u32_e32 v2, s56, v9
	v_ashrrev_i32_e32 v3, 31, v2
	v_mul_lo_u32 v4, s24, v3
	v_mul_lo_u32 v5, s25, v2
	v_mad_u64_u32 v[2:3], s[18:19], s24, v2, 0
	v_add3_u32 v3, v3, v4, v5
	v_lshl_add_u64 v[2:3], v[2:3], 2, v[6:7]
	global_load_dwordx4 v[136:139], v[2:3], off
	v_lshl_add_u64 v[2:3], v[2:3], 0, s[100:101]
	global_load_dwordx4 v[140:143], v[2:3], off
	v_lshl_add_u64 v[2:3], v[2:3], 0, s[100:101]
	global_load_dwordx4 v[144:147], v[2:3], off
	v_lshl_add_u64 v[2:3], v[2:3], 0, s[100:101]
	global_load_dwordx4 v[148:151], v[2:3], off
	v_lshl_add_u64 v[2:3], v[2:3], 0, s[100:101]
	global_load_dwordx4 v[152:155], v[2:3], off
	v_lshl_add_u64 v[2:3], v[2:3], 0, s[100:101]
	global_load_dwordx4 v[156:159], v[2:3], off
	v_lshl_add_u64 v[2:3], v[2:3], 0, s[100:101]
	global_load_dwordx4 v[160:163], v[2:3], off
	v_lshl_add_u64 v[2:3], v[2:3], 0, s[100:101]
	global_load_dwordx4 v[164:167], v[2:3], off
.LconvB_skip:
	s_or_b64 exec, exec, s[26:27]
	v_lshl_add_u32 v1, v1, 2, 0
	v_mul_lo_u32 v10, v9, s16
	v_add_u32_e32 v10, v1, v10
	s_waitcnt vmcnt(7)
	ds_write2_b32 v10, v136, v137 offset1:1
	ds_write2_b32 v10, v138, v139 offset0:2 offset1:3
	s_waitcnt vmcnt(6)
	v_add_u32_e32 v4, 0x2020, v10
	ds_write2_b32 v4, v140, v141 offset1:1
	ds_write2_b32 v4, v142, v143 offset0:2 offset1:3
	s_waitcnt vmcnt(5)
	v_add_u32_e32 v4, 0x4040, v10
	ds_write2_b32 v4, v144, v145 offset1:1
	ds_write2_b32 v4, v146, v147 offset0:2 offset1:3
	s_waitcnt vmcnt(4)
	v_add_u32_e32 v4, 0x6060, v10
	ds_write2_b32 v4, v148, v149 offset1:1
	ds_write2_b32 v4, v150, v151 offset0:2 offset1:3
	s_waitcnt vmcnt(3)
	v_add_u32_e32 v4, 0x8080, v10
	ds_write2_b32 v4, v152, v153 offset1:1
	ds_write2_b32 v4, v154, v155 offset0:2 offset1:3
	s_waitcnt vmcnt(2)
	v_add_u32_e32 v4, 0xa0a0, v10
	ds_write2_b32 v4, v156, v157 offset1:1
	ds_write2_b32 v4, v158, v159 offset0:2 offset1:3
	s_waitcnt vmcnt(1)
	v_add_u32_e32 v4, 0xc0c0, v10
	ds_write2_b32 v4, v160, v161 offset1:1
	ds_write2_b32 v4, v162, v163 offset0:2 offset1:3
	s_waitcnt vmcnt(0)
	v_add_u32_e32 v4, 0xe0e0, v10
	ds_write2_b32 v4, v164, v165 offset1:1
	ds_write2_b32 v4, v166, v167 offset0:2 offset1:3
	v_lshlrev_b32_e32 v0, 3, v8
	v_and_b32_e32 v0, 56, v0
	v_mad_u32_u24 v2, v0, s16, 0
	v_ashrrev_i32_e32 v1, 3, v8
	v_lshl_add_u32 v11, v1, 2, v2
	s_waitcnt lgkmcnt(0)
	s_barrier
	ds_read_b32 v3, v11
	ds_read_b32 v4, v11 offset:1028
	ds_read_b32 v5, v11 offset:2056
	ds_read_b32 v6, v11 offset:3084
	ds_read_b32 v7, v11 offset:4112
	ds_read_b32 v9, v11 offset:5140
	ds_read_b32 v10, v11 offset:6168
	ds_read_b32 v11, v11 offset:7196
	s_xor_b64 s[22:23], s[22:23], -1
	s_mov_b64 s[24:25], -1
	s_and_b64 vcc, exec, s[22:23]
	s_cbranch_vccz .LBB0_559
	v_add_u32_e32 v12, s36, v1
	v_lshlrev_b32_e32 v13, 1, v12
	v_and_b32_e32 v12, 0x7f, v12
	v_and_b32_e32 v13, 0xffffff00, v13
	v_or_b32_e32 v12, s9, v12
	v_add_u32_e32 v12, v12, v13
	s_mov_b64 s[24:25], 0

.LBB0_1805:
	s_cmpk_gt_i32 s10, 0xff
	s_cbranch_scc0 .LBB0_1810
	s_add_i32 s6, s10, 0xffffff00
	v_mov_b32_e32 v50, v230
	s_lshl_b32 s7, s10, 7
	s_lshr_b32 s12, s6, 2
	s_and_b32 s11, s7, 0x180
	v_and_b32_e32 v3, 31, v50
	v_mov_b32_e32 v6, s23
	s_movk_i32 s7, 0x840
	s_lshl_b32 s6, s12, 8
	v_lshlrev_b32_e32 v48, 4, v3
	v_lshl_add_u32 v2, v3, 3, 0
	v_mad_u32_u24 v6, v3, s7, v6
	v_ashrrev_i32_e32 v3, 5, v50
	v_add_u32_e32 v8, s6, v3
	v_readlane_b32 s44, v253, 21
	v_ashrrev_i32_e32 v9, 31, v8
	v_readlane_b32 s58, v253, 35
	v_readlane_b32 s59, v253, 36
	v_lshlrev_b64 v[12:13], 11, v[8:9]
	s_lshl_b32 s90, s11, 2
	v_lshl_add_u64 v[4:5], s[58:59], 0, v[48:49]
	v_or_b32_e32 v12, s90, v12
	v_lshl_add_u64 v[8:9], v[4:5], 0, v[12:13]
	s_waitcnt vmcnt(0) lgkmcnt(0)
	s_barrier
	global_load_dwordx4 v[112:115], v[8:9], off
	v_readlane_b32 s45, v253, 22
	v_readlane_b32 s46, v253, 23
	v_readlane_b32 s47, v253, 24
	v_readlane_b32 s48, v253, 25
	v_readlane_b32 s49, v253, 26
	v_readlane_b32 s50, v253, 27
	v_readlane_b32 s51, v253, 28
	v_readlane_b32 s52, v253, 29
	v_readlane_b32 s53, v253, 30
	v_readlane_b32 s54, v253, 31
	v_readlane_b32 s55, v253, 32
	v_readlane_b32 s56, v253, 33
	v_readlane_b32 s57, v253, 34
	v_readlane_b32 s44, v253, 37
	v_readlane_b32 s45, v253, 38
	v_readlane_b32 s46, v253, 39
	v_readlane_b32 s47, v253, 40
	v_readlane_b32 s48, v253, 41
	v_readlane_b32 s49, v253, 42
	v_readlane_b32 s50, v253, 43
	v_readlane_b32 s51, v253, 44
	v_readlane_b32 s52, v253, 45
	v_readlane_b32 s53, v253, 46
	v_readlane_b32 s54, v253, 47
	v_readlane_b32 s55, v253, 48
	v_readlane_b32 s56, v253, 49
	v_readlane_b32 s57, v253, 50
	v_readlane_b32 s58, v253, 51
	v_readlane_b32 s59, v253, 52
	s_mov_b64 s[100:101], 0x8000
	v_lshl_add_u64 v[0:1], s[44:45], 0, v[48:49]
	v_lshl_add_u64 v[0:1], v[0:1], 0, v[12:13]
	global_load_dwordx4 v[176:179], v[0:1], off
	v_lshl_add_u64 v[8:9], v[8:9], 0, s[100:101]
	global_load_dwordx4 v[116:119], v[8:9], off
	v_lshl_add_u64 v[0:1], v[0:1], 0, s[100:101]
	global_load_dwordx4 v[180:183], v[0:1], off
	v_lshl_add_u64 v[8:9], v[8:9], 0, s[100:101]
	global_load_dwordx4 v[120:123], v[8:9], off
	v_lshl_add_u64 v[0:1], v[0:1], 0, s[100:101]
	global_load_dwordx4 v[184:187], v[0:1], off
	v_lshl_add_u64 v[8:9], v[8:9], 0, s[100:101]
	global_load_dwordx4 v[124:127], v[8:9], off
	v_lshl_add_u64 v[0:1], v[0:1], 0, s[100:101]
	global_load_dwordx4 v[188:191], v[0:1], off
	v_lshl_add_u64 v[8:9], v[8:9], 0, s[100:101]
	global_load_dwordx4 v[128:131], v[8:9], off
	v_lshl_add_u64 v[0:1], v[0:1], 0, s[100:101]
	global_load_dwordx4 v[192:195], v[0:1], off
	v_lshl_add_u64 v[8:9], v[8:9], 0, s[100:101]
	global_load_dwordx4 v[132:135], v[8:9], off
	v_lshl_add_u64 v[0:1], v[0:1], 0, s[100:101]
	global_load_dwordx4 v[196:199], v[0:1], off
	v_lshl_add_u64 v[8:9], v[8:9], 0, s[100:101]
	global_load_dwordx4 v[136:139], v[8:9], off
	v_lshl_add_u64 v[0:1], v[0:1], 0, s[100:101]
	global_load_dwordx4 v[200:203], v[0:1], off
	v_lshl_add_u64 v[8:9], v[8:9], 0, s[100:101]
	global_load_dwordx4 v[140:143], v[8:9], off
	v_lshl_add_u64 v[0:1], v[0:1], 0, s[100:101]
	global_load_dwordx4 v[204:207], v[0:1], off
	v_lshl_add_u64 v[8:9], v[8:9], 0, s[100:101]
	global_load_dwordx4 v[144:147], v[8:9], off
	v_lshl_add_u64 v[0:1], v[0:1], 0, s[100:101]
	global_load_dwordx4 v[208:211], v[0:1], off
	v_lshl_add_u64 v[8:9], v[8:9], 0, s[100:101]
	global_load_dwordx4 v[148:151], v[8:9], off
	v_lshl_add_u64 v[0:1], v[0:1], 0, s[100:101]
	global_load_dwordx4 v[212:215], v[0:1], off
	v_lshl_add_u64 v[8:9], v[8:9], 0, s[100:101]
	global_load_dwordx4 v[152:155], v[8:9], off
	v_lshl_add_u64 v[0:1], v[0:1], 0, s[100:101]
	global_load_dwordx4 v[216:219], v[0:1], off
	v_lshl_add_u64 v[8:9], v[8:9], 0, s[100:101]
	global_load_dwordx4 v[156:159], v[8:9], off
	v_lshl_add_u64 v[0:1], v[0:1], 0, s[100:101]
	global_load_dwordx4 v[220:223], v[0:1], off
	v_lshl_add_u64 v[8:9], v[8:9], 0, s[100:101]
	global_load_dwordx4 v[160:163], v[8:9], off
	v_lshl_add_u64 v[0:1], v[0:1], 0, s[100:101]
	global_load_dwordx4 v[224:227], v[0:1], off
	v_lshl_add_u64 v[8:9], v[8:9], 0, s[100:101]
	global_load_dwordx4 v[164:167], v[8:9], off
	v_lshl_add_u64 v[0:1], v[0:1], 0, s[100:101]
	global_load_dwordx4 v[232:235], v[0:1], off
	v_lshl_add_u64 v[8:9], v[8:9], 0, s[100:101]
	global_load_dwordx4 v[168:171], v[8:9], off
	v_lshl_add_u64 v[0:1], v[0:1], 0, s[100:101]
	global_load_dwordx4 v[236:239], v[0:1], off
	v_lshl_add_u64 v[8:9], v[8:9], 0, s[100:101]
	global_load_dwordx4 v[172:175], v[8:9], off
	v_lshl_add_u64 v[0:1], v[0:1], 0, s[100:101]
	global_load_dwordx4 v[240:243], v[0:1], off
	v_mad_u32_u24 v10, v3, s24, v2
	v_lshl_add_u32 v7, v3, 1, v6
	s_waitcnt vmcnt(31)
	v_cvt_pk_bf16_f32 v16, v112, v113
	v_cvt_pk_bf16_f32 v17, v114, v115
	ds_write_b64 v10, v[16:17]
	s_waitcnt vmcnt(30)
	v_cvt_pk_bf16_f32 v18, v176, v177
	v_cvt_pk_bf16_f32 v19, v178, v179
	ds_write_b16 v7, v18
	ds_write_b16_d16_hi v7, v18 offset:528
	ds_write_b16 v7, v19 offset:1056
	ds_write_b16_d16_hi v7, v19 offset:1584
	s_waitcnt vmcnt(29)
	v_cvt_pk_bf16_f32 v16, v116, v117
	v_cvt_pk_bf16_f32 v17, v118, v119
	ds_write_b64 v10, v[16:17] offset:4352
	s_waitcnt vmcnt(28)
	v_cvt_pk_bf16_f32 v18, v180, v181
	v_cvt_pk_bf16_f32 v19, v182, v183
	ds_write_b16 v7, v18 offset:32
	ds_write_b16_d16_hi v7, v18 offset:560
	ds_write_b16 v7, v19 offset:1088
	ds_write_b16_d16_hi v7, v19 offset:1616
	s_waitcnt vmcnt(27)
	v_cvt_pk_bf16_f32 v16, v120, v121
	v_cvt_pk_bf16_f32 v17, v122, v123
	ds_write_b64 v10, v[16:17] offset:8704
	s_waitcnt vmcnt(26)
	v_cvt_pk_bf16_f32 v18, v184, v185
	v_cvt_pk_bf16_f32 v19, v186, v187
	ds_write_b16 v7, v18 offset:64
	ds_write_b16_d16_hi v7, v18 offset:592
	ds_write_b16 v7, v19 offset:1120
	ds_write_b16_d16_hi v7, v19 offset:1648
	s_waitcnt vmcnt(25)
	v_cvt_pk_bf16_f32 v16, v124, v125
	v_cvt_pk_bf16_f32 v17, v126, v127
	ds_write_b64 v10, v[16:17] offset:13056
	s_waitcnt vmcnt(24)
	v_cvt_pk_bf16_f32 v18, v188, v189
	v_cvt_pk_bf16_f32 v19, v190, v191
	ds_write_b16 v7, v18 offset:96
	ds_write_b16_d16_hi v7, v18 offset:624
	ds_write_b16 v7, v19 offset:1152
	ds_write_b16_d16_hi v7, v19 offset:1680
	s_waitcnt vmcnt(23)
	v_cvt_pk_bf16_f32 v16, v128, v129
	v_cvt_pk_bf16_f32 v17, v130, v131
	ds_write_b64 v10, v[16:17] offset:17408
	s_waitcnt vmcnt(22)
	v_cvt_pk_bf16_f32 v18, v192, v193
	v_cvt_pk_bf16_f32 v19, v194, v195
	ds_write_b16 v7, v18 offset:128
	ds_write_b16_d16_hi v7, v18 offset:656
	ds_write_b16 v7, v19 offset:1184
	ds_write_b16_d16_hi v7, v19 offset:1712
	s_waitcnt vmcnt(21)
	v_cvt_pk_bf16_f32 v16, v132, v133
	v_cvt_pk_bf16_f32 v17, v134, v135
	ds_write_b64 v10, v[16:17] offset:21760
	s_waitcnt vmcnt(20)
	v_cvt_pk_bf16_f32 v18, v196, v197
	v_cvt_pk_bf16_f32 v19, v198, v199
	ds_write_b16 v7, v18 offset:160
	ds_write_b16_d16_hi v7, v18 offset:688
	ds_write_b16 v7, v19 offset:1216
	ds_write_b16_d16_hi v7, v19 offset:1744
	s_waitcnt vmcnt(19)
	v_cvt_pk_bf16_f32 v16, v136, v137
	v_cvt_pk_bf16_f32 v17, v138, v139
	ds_write_b64 v10, v[16:17] offset:26112
	s_waitcnt vmcnt(18)
	v_cvt_pk_bf16_f32 v18, v200, v201
	v_cvt_pk_bf16_f32 v19, v202, v203
	ds_write_b16 v7, v18 offset:192
	ds_write_b16_d16_hi v7, v18 offset:720
	ds_write_b16 v7, v19 offset:1248
	ds_write_b16_d16_hi v7, v19 offset:1776
	s_waitcnt vmcnt(17)
	v_cvt_pk_bf16_f32 v16, v140, v141
	v_cvt_pk_bf16_f32 v17, v142, v143
	ds_write_b64 v10, v[16:17] offset:30464
	s_waitcnt vmcnt(16)
	v_cvt_pk_bf16_f32 v18, v204, v205
	v_cvt_pk_bf16_f32 v19, v206, v207
	ds_write_b16 v7, v18 offset:224
	ds_write_b16_d16_hi v7, v18 offset:752
	ds_write_b16 v7, v19 offset:1280
	ds_write_b16_d16_hi v7, v19 offset:1808
	s_waitcnt vmcnt(15)
	v_cvt_pk_bf16_f32 v16, v144, v145
	v_cvt_pk_bf16_f32 v17, v146, v147
	ds_write_b64 v10, v[16:17] offset:34816
	s_waitcnt vmcnt(14)
	v_cvt_pk_bf16_f32 v18, v208, v209
	v_cvt_pk_bf16_f32 v19, v210, v211
	ds_write_b16 v7, v18 offset:256
	ds_write_b16_d16_hi v7, v18 offset:784
	ds_write_b16 v7, v19 offset:1312
	ds_write_b16_d16_hi v7, v19 offset:1840
	s_waitcnt vmcnt(13)
	v_cvt_pk_bf16_f32 v16, v148, v149
	v_cvt_pk_bf16_f32 v17, v150, v151
	ds_write_b64 v10, v[16:17] offset:39168
	s_waitcnt vmcnt(12)
	v_cvt_pk_bf16_f32 v18, v212, v213
	v_cvt_pk_bf16_f32 v19, v214, v215
	ds_write_b16 v7, v18 offset:288
	ds_write_b16_d16_hi v7, v18 offset:816
	ds_write_b16 v7, v19 offset:1344
	ds_write_b16_d16_hi v7, v19 offset:1872
	s_waitcnt vmcnt(11)
	v_cvt_pk_bf16_f32 v16, v152, v153
	v_cvt_pk_bf16_f32 v17, v154, v155
	ds_write_b64 v10, v[16:17] offset:43520
	s_waitcnt vmcnt(10)
	v_cvt_pk_bf16_f32 v18, v216, v217
	v_cvt_pk_bf16_f32 v19, v218, v219
	ds_write_b16 v7, v18 offset:320
	ds_write_b16_d16_hi v7, v18 offset:848
	ds_write_b16 v7, v19 offset:1376
	ds_write_b16_d16_hi v7, v19 offset:1904
	s_waitcnt vmcnt(9)
	v_cvt_pk_bf16_f32 v16, v156, v157
	v_cvt_pk_bf16_f32 v17, v158, v159
	ds_write_b64 v10, v[16:17] offset:47872
	s_waitcnt vmcnt(8)
	v_cvt_pk_bf16_f32 v18, v220, v221
	v_cvt_pk_bf16_f32 v19, v222, v223
	ds_write_b16 v7, v18 offset:352
	ds_write_b16_d16_hi v7, v18 offset:880
	ds_write_b16 v7, v19 offset:1408
	ds_write_b16_d16_hi v7, v19 offset:1936
	s_waitcnt vmcnt(7)
	v_cvt_pk_bf16_f32 v16, v160, v161
	v_cvt_pk_bf16_f32 v17, v162, v163
	ds_write_b64 v10, v[16:17] offset:52224
	s_waitcnt vmcnt(6)
	v_cvt_pk_bf16_f32 v18, v224, v225
	v_cvt_pk_bf16_f32 v19, v226, v227
	ds_write_b16 v7, v18 offset:384
	ds_write_b16_d16_hi v7, v18 offset:912
	ds_write_b16 v7, v19 offset:1440
	ds_write_b16_d16_hi v7, v19 offset:1968
	s_waitcnt vmcnt(5)
	v_cvt_pk_bf16_f32 v16, v164, v165
	v_cvt_pk_bf16_f32 v17, v166, v167
	ds_write_b64 v10, v[16:17] offset:56576
	s_waitcnt vmcnt(4)
	v_cvt_pk_bf16_f32 v18, v232, v233
	v_cvt_pk_bf16_f32 v19, v234, v235
	ds_write_b16 v7, v18 offset:416
	ds_write_b16_d16_hi v7, v18 offset:944
	ds_write_b16 v7, v19 offset:1472
	ds_write_b16_d16_hi v7, v19 offset:2000
	s_waitcnt vmcnt(3)
	v_cvt_pk_bf16_f32 v16, v168, v169
	v_cvt_pk_bf16_f32 v17, v170, v171
	ds_write_b64 v10, v[16:17] offset:60928
	s_waitcnt vmcnt(2)
	v_cvt_pk_bf16_f32 v18, v236, v237
	v_cvt_pk_bf16_f32 v19, v238, v239
	ds_write_b16 v7, v18 offset:448
	ds_write_b16_d16_hi v7, v18 offset:976
	ds_write_b16 v7, v19 offset:1504
	ds_write_b16_d16_hi v7, v19 offset:2032
	s_waitcnt vmcnt(1)
	v_cvt_pk_bf16_f32 v16, v172, v173
	v_cvt_pk_bf16_f32 v17, v174, v175
	ds_write_b64 v10, v[16:17] offset:65280
	s_waitcnt vmcnt(0)
	v_cvt_pk_bf16_f32 v18, v240, v241
	v_cvt_pk_bf16_f32 v19, v242, v243
	ds_write_b16 v7, v18 offset:480
	ds_write_b16_d16_hi v7, v18 offset:1008
	ds_write_b16 v7, v19 offset:1536
	ds_write_b16_d16_hi v7, v19 offset:2064
	v_readfirstlane_b32 s8, v50
	s_cmp_lt_u32 s8, 64
	s_mov_b64 s[8:9], 0
	s_mov_b64 s[6:7], 0
	s_waitcnt lgkmcnt(0)
	s_barrier
	s_cbranch_scc0 .LBB0_1811
	s_lshl_b32 s8, s12, 13
	v_and_b32_e32 v29, 15, v50
	s_add_i32 s8, s8, 0x400000
	v_lshl_or_b32 v48, v29, 9, s8
	v_bfe_u32 v54, v50, 4, 2
	v_lshl_add_u64 v[0:1], v[48:49], 2, s[84:85]
	v_lshl_add_u64 v[0:1], v[0:1], 0, s[90:91]
	v_lshlrev_b32_e32 v2, 5, v54
	v_mov_b32_e32 v3, v49
	v_lshl_add_u64 v[24:25], v[0:1], 0, v[2:3]
	v_add_co_u32_e32 v26, vcc, s25, v24
	v_lshl_add_u64 v[12:13], v[24:25], 0, s[92:93]
	s_nop 0
	v_addc_co_u32_e32 v27, vcc, 0, v25, vcc
	global_load_dwordx4 v[112:115], v[24:25], off offset:16
	global_load_dwordx4 v[116:119], v[24:25], off offset:0
	global_load_dwordx4 v[120:123], v[26:27], off offset:0
	v_lshl_add_u64 v[20:21], v[24:25], 0, s[92:93]
	global_load_dwordx4 v[124:127], v[20:21], off offset:16
	global_load_dwordx4 v[128:131], v[24:25], off offset:144
	global_load_dwordx4 v[132:135], v[24:25], off offset:128
	global_load_dwordx4 v[136:139], v[26:27], off offset:128
	v_lshl_add_u64 v[20:21], v[24:25], 0, s[94:95]
	global_load_dwordx4 v[140:143], v[20:21], off offset:16
	global_load_dwordx4 v[144:147], v[24:25], off offset:272
	global_load_dwordx4 v[148:151], v[24:25], off offset:256
	global_load_dwordx4 v[152:155], v[26:27], off offset:256
	v_lshl_add_u64 v[20:21], v[24:25], 0, s[2:3]
	global_load_dwordx4 v[156:159], v[20:21], off offset:16
	global_load_dwordx4 v[160:163], v[24:25], off offset:400
	global_load_dwordx4 v[164:167], v[24:25], off offset:384
	global_load_dwordx4 v[168:171], v[26:27], off offset:384
	v_lshl_add_u64 v[20:21], v[24:25], 0, s[4:5]
	global_load_dwordx4 v[172:175], v[20:21], off offset:16
	s_waitcnt vmcnt(0)
	v_pk_add_f32 v[116:117], v[116:117], v[120:121]
	v_pk_add_f32 v[118:119], v[118:119], v[122:123]
	v_pk_add_f32 v[112:113], v[112:113], v[124:125]
	v_pk_add_f32 v[114:115], v[114:115], v[126:127]
	v_cvt_pk_bf16_f32 v0, v116, v117
	v_cvt_pk_bf16_f32 v1, v118, v119
	v_cvt_pk_bf16_f32 v2, v112, v113
	v_cvt_pk_bf16_f32 v3, v114, v115
	v_pk_add_f32 v[132:133], v[132:133], v[136:137]
	v_pk_add_f32 v[134:135], v[134:135], v[138:139]
	v_pk_add_f32 v[128:129], v[128:129], v[140:141]
	v_pk_add_f32 v[130:131], v[130:131], v[142:143]
	v_cvt_pk_bf16_f32 v4, v132, v133
	v_cvt_pk_bf16_f32 v5, v134, v135
	v_cvt_pk_bf16_f32 v6, v128, v129
	v_cvt_pk_bf16_f32 v7, v130, v131
	v_pk_add_f32 v[148:149], v[148:149], v[152:153]
	v_pk_add_f32 v[150:151], v[150:151], v[154:155]
	v_pk_add_f32 v[144:145], v[144:145], v[156:157]
	v_pk_add_f32 v[146:147], v[146:147], v[158:159]
	v_cvt_pk_bf16_f32 v8, v148, v149
	v_cvt_pk_bf16_f32 v9, v150, v151
	v_cvt_pk_bf16_f32 v10, v144, v145
	v_cvt_pk_bf16_f32 v11, v146, v147
	v_pk_add_f32 v[164:165], v[164:165], v[168:169]
	v_pk_add_f32 v[166:167], v[166:167], v[170:171]
	v_pk_add_f32 v[160:161], v[160:161], v[172:173]
	v_pk_add_f32 v[162:163], v[162:163], v[174:175]
	v_cvt_pk_bf16_f32 v16, v164, v165
	v_cvt_pk_bf16_f32 v17, v166, v167
	v_cvt_pk_bf16_f32 v18, v160, v161
	v_cvt_pk_bf16_f32 v19, v162, v163
	v_and_b32_e32 v28, 63, v50
	v_mov_b32_e32 v60, 0
	v_mov_b32_e32 v62, 0xff800000
	s_mov_b32 s8, 4
	v_mov_b32_e32 v44, 0
	v_mov_b32_e32 v45, v60
	v_mov_b32_e32 v46, v60
	v_mov_b32_e32 v47, v60
	v_mov_b32_e32 v40, 0
	v_mov_b32_e32 v41, v60
	v_mov_b32_e32 v42, v60
	v_mov_b32_e32 v43, v60
	v_mov_b32_e32 v36, 0
	v_mov_b32_e32 v37, v60
	v_mov_b32_e32 v38, v60
	v_mov_b32_e32 v39, v60
	v_mov_b32_e32 v30, v60
	v_mov_b32_e32 v31, v60
	v_mov_b32_e32 v32, 0
	v_mov_b32_e32 v33, v60
	v_mov_b32_e32 v34, v60
	v_mov_b32_e32 v35, v60
	v_and_b32_e32 v15, 64, v53
	v_xor_b32_e32 v14, 16, v53
	v_add_u32_e32 v15, 64, v15
	v_cmp_lt_i32_e32 vcc, v14, v15
	s_nop 1
	v_mov_b32_e32 v24, 0
	v_cndmask_b32_e32 v14, v53, v14, vcc
	v_lshlrev_b32_e32 v51, 2, v14
	v_xor_b32_e32 v14, 32, v53
	v_cmp_lt_i32_e32 vcc, v14, v15
	s_nop 1
	v_and_b32_e32 v12, 48, v50
	v_cndmask_b32_e32 v14, v53, v14, vcc
	v_lshlrev_b32_e32 v55, 2, v14
	v_lshrrev_b32_e32 v14, 1, v50
	v_or_b32_e32 v13, 48, v28
	v_and_b32_e32 v14, 24, v14
	v_or_b32_e32 v15, 0x70, v28
	v_mad_u32_u24 v50, v15, s26, v14
	v_mad_u32_u24 v56, v13, s26, v14
	v_mad_u32_u24 v57, v29, s26, v14
	v_mad_u32_u24 v58, v13, s24, v12
	v_mad_u32_u24 v59, v29, s24, v12
	v_mov_b32_e32 v28, 0
	v_mov_b32_e32 v29, v60
	v_mov_b32_e32 v25, v60
	v_mov_b32_e32 v26, v60
	v_mov_b32_e32 v27, v60
	v_mov_b32_e32 v20, 0
	v_mov_b32_e32 v21, v60
	v_mov_b32_e32 v22, v60
	v_mov_b32_e32 v23, v60
	v_mov_b32_e32 v12, 0
	v_mov_b32_e32 v13, v60
	v_mov_b32_e32 v14, v60
	v_mov_b32_e32 v15, v60
